# stacked: DSA score steps with VALU filling the MFMA wait window and v_max_f32 relu
# speedup vs baseline: 1.0066x; 1.0021x over previous
; DI f32x16 mfma32(bf16x8 a, bf16x8 b, f32x16 c) { return __builtin_amdgcn_mfma_f32_32x32x16_bf16(a, b, c, 0, 0, 0); }
; DI u32 mono_key(float f) { u32 u = __float_as_uint(f); return (u & 0x80000000u) ? ~u : (u | 0x80000000u); }
; DI void dsa_item(const Params& p, int l, int tile32, int b, char* smem) {
;     ...
;       for (int t = 0; t < 4; ++t) {
;         const int key = (g * 4 + t) * 32 + c31;
;         f32x16 acc;
; #pragma unroll
;         for (int j = 0; j < 16; ++j) acc[j] = 0.f;
; #pragma unroll
;         for (int s = 0; s < 4; ++s) acc = mfma32(qa[s], kc[t][s], acc);
;         f32x2 ss2 = f32x2{0.f, 0.f};
; #pragma unroll
;         for (int hq = 0; hq < 8; ++hq) {
;           const f32x2 rr = f32x2{__builtin_amdgcn_fmed3f(acc[2 * hq], 0.f, 3.0e38f), __builtin_amdgcn_fmed3f(acc[2 * hq + 1], 0.f, 3.0e38f)};
;           ss2 = __builtin_elementwise_fma(wq2[hq], rr, ss2);
;         }
;         const float s0 = ss2.x, s1 = ss2.y;
;         const u32 k0 = mono_key(s0), k1 = mono_key(s1);
;         const bool c0 = (key <= qpos0) && (k0 > tauA), c1 = (key <= qpos0 + 1) && (k1 > tauB);
;         const u64 m0 = __ballot(c0), m1 = __ballot(c1);
;         if (m0 | m1) {
;           const u32 h0 = hh ? (u32)(m0 >> 32) : (u32)m0, h1 = hh ? (u32)(m1 >> 32) : (u32)m1;
;           const int pA = (hh ? cnt2 : cnt0) + __popc(h0 & lmask), pB = (hh ? cnt3 : cnt1) + __popc(h1 & lmask);
;           if (c0) { ckey[(2 * hh) * DCAP + pA] = k0; cidx[(2 * hh) * DCAP + pA] = (u16)key; }
;           if (c1) { ckey[(2 * hh + 1) * DCAP + pB] = k1; cidx[(2 * hh + 1) * DCAP + pB] = (u16)key; }
;           cnt0 += __popc((u32)m0); cnt2 += __popc((u32)(m0 >> 32));
;           cnt1 += __popc((u32)m1); cnt3 += __popc((u32)(m1 >> 32));
;         }
.LBB0_499:
	s_or_b64 exec, exec, s[2:3]
	v_mfma_f32_32x32x16_bf16 v[2:17], v[18:21], v[2:5], 0
	v_cndmask_b32_e32 v0, v223, v224, vcc
	v_mfma_f32_32x32x16_bf16 v[2:17], v[22:25], v[98:101], v[2:17]
	v_mfma_f32_32x32x16_bf16 v[2:17], v[26:29], v[94:97], v[2:17]
	v_mfma_f32_32x32x16_bf16 v[2:17], v[30:33], v[90:93], v[2:17]
	v_lshl_or_b32 v95, s54, 7, v192
	v_cndmask_b32_e32 v94, v221, v222, vcc
	v_cmp_le_i32_e64 s[0:1], v95, v217
	v_cmp_le_i32_e64 s[2:3], v95, v219
	s_nop 7
	v_max_f32_e32 v2, 0, v2
	v_max_f32_e32 v3, 0, v3
	v_max_f32_e32 v4, 0, v4
	v_max_f32_e32 v5, 0, v5
	v_fma_f32 v2, v178, v2, 0
	v_fma_f32 v3, v179, v3, 0
	v_max_f32_e32 v6, 0, v6
	v_max_f32_e32 v7, 0, v7
	v_fmac_f32_e32 v2, v38, v4
	v_fmac_f32_e32 v3, v39, v5
	v_max_f32_e32 v8, 0, v8
	v_max_f32_e32 v9, 0, v9
	v_fmac_f32_e32 v2, v180, v6
	v_fmac_f32_e32 v3, v181, v7
	v_max_f32_e32 v10, 0, v10
	v_max_f32_e32 v11, 0, v11
	v_fmac_f32_e32 v2, v40, v8
	v_fmac_f32_e32 v3, v41, v9
	v_max_f32_e32 v12, 0, v12
	v_max_f32_e32 v13, 0, v13
	v_fmac_f32_e32 v2, v182, v10
	v_fmac_f32_e32 v3, v183, v11
	v_max_f32_e32 v14, 0, v14
	v_max_f32_e32 v15, 0, v15
	v_fmac_f32_e32 v2, v34, v12
	v_fmac_f32_e32 v3, v35, v13
	v_max_f32_e32 v16, 0, v16
	v_max_f32_e32 v17, 0, v17
	v_fmac_f32_e32 v2, v184, v14
	v_fmac_f32_e32 v3, v185, v15
	v_fma_f32 v4, v36, v16, v2
	v_fma_f32 v5, v37, v17, v3
	v_ashrrev_i32_e32 v2, 31, v4
	v_ashrrev_i32_e32 v6, 31, v5
	v_or_b32_e32 v2, 0x80000000, v2
	v_or_b32_e32 v6, 0x80000000, v6
	v_xor_b32_e32 v3, v4, v2
	v_xor_b32_e32 v2, v5, v6
	v_cmp_gt_u32_e64 s[4:5], v3, v0
	v_cmp_gt_u32_e64 s[6:7], v2, v94
	s_and_b64 s[10:11], s[0:1], s[4:5]
	s_and_b64 s[4:5], s[2:3], s[6:7]
	s_or_b64 s[6:7], s[10:11], s[4:5]
	s_cbranch_scc0 .LBB0_505
	s_and_b64 s[0:1], s[10:11], exec
	s_and_b64 s[2:3], s[4:5], exec
	s_and_saveexec_b64 s[6:7], s[10:11]
	s_cbranch_execz .LBB0_502
	v_mov_b32_e32 v4, s1
	v_mov_b32_e32 v5, s0
	v_cndmask_b32_e32 v4, v4, v5, vcc
	v_and_b32_e32 v4, v4, v218
	v_bcnt_u32_b32 v4, v4, 0
	v_cndmask_b32_e32 v5, v187, v173, vcc
	v_add3_u32 v4, v5, v214, v4
	v_lshl_add_u32 v5, v4, 2, v190
	ds_write_b32 v5, v3
	v_lshlrev_b32_e32 v3, 1, v4
	v_sub_u32_e32 v3, v5, v3
	ds_write_b16 v3, v95 offset:10240

; DI f32x16 mfma32(bf16x8 a, bf16x8 b, f32x16 c) { return __builtin_amdgcn_mfma_f32_32x32x16_bf16(a, b, c, 0, 0, 0); }
; DI u32 mono_key(float f) { u32 u = __float_as_uint(f); return (u & 0x80000000u) ? ~u : (u | 0x80000000u); }
; DI void dsa_item(const Params& p, int l, int tile32, int b, char* smem) {
;     ...
;       for (int t = 0; t < 4; ++t) {
;         const int key = (g * 4 + t) * 32 + c31;
;         f32x16 acc;
; #pragma unroll
;         for (int j = 0; j < 16; ++j) acc[j] = 0.f;
; #pragma unroll
;         for (int s = 0; s < 4; ++s) acc = mfma32(qa[s], kc[t][s], acc);
;         f32x2 ss2 = f32x2{0.f, 0.f};
; #pragma unroll
;         for (int hq = 0; hq < 8; ++hq) {
;           const f32x2 rr = f32x2{__builtin_amdgcn_fmed3f(acc[2 * hq], 0.f, 3.0e38f), __builtin_amdgcn_fmed3f(acc[2 * hq + 1], 0.f, 3.0e38f)};
;           ss2 = __builtin_elementwise_fma(wq2[hq], rr, ss2);
;         }
;         const float s0 = ss2.x, s1 = ss2.y;
;         const u32 k0 = mono_key(s0), k1 = mono_key(s1);
;         const bool c0 = (key <= qpos0) && (k0 > tauA), c1 = (key <= qpos0 + 1) && (k1 > tauB);
;         const u64 m0 = __ballot(c0), m1 = __ballot(c1);
;         if (m0 | m1) {
;           const u32 h0 = hh ? (u32)(m0 >> 32) : (u32)m0, h1 = hh ? (u32)(m1 >> 32) : (u32)m1;
;           const int pA = (hh ? cnt2 : cnt0) + __popc(h0 & lmask), pB = (hh ? cnt3 : cnt1) + __popc(h1 & lmask);
;           if (c0) { ckey[(2 * hh) * DCAP + pA] = k0; cidx[(2 * hh) * DCAP + pA] = (u16)key; }
;           if (c1) { ckey[(2 * hh + 1) * DCAP + pB] = k1; cidx[(2 * hh + 1) * DCAP + pB] = (u16)key; }
;           cnt0 += __popc((u32)m0); cnt2 += __popc((u32)(m0 >> 32));
;           cnt1 += __popc((u32)m1); cnt3 += __popc((u32)(m1 >> 32));
;         }
.LBB0_505:
	v_mfma_f32_32x32x16_bf16 v[2:17], v[18:21], v[86:89], 0
	v_mfma_f32_32x32x16_bf16 v[2:17], v[22:25], v[82:85], v[2:17]
	v_mfma_f32_32x32x16_bf16 v[2:17], v[26:29], v[78:81], v[2:17]
	v_mfma_f32_32x32x16_bf16 v[2:17], v[30:33], v[74:77], v[2:17]
	v_or_b32_e32 v78, 32, v95
	v_cmp_le_i32_e64 s[0:1], v78, v217
	v_cmp_le_i32_e64 s[2:3], v78, v219
	s_nop 8
	v_max_f32_e32 v2, 0, v2
	v_max_f32_e32 v3, 0, v3
	v_max_f32_e32 v4, 0, v4
	v_max_f32_e32 v5, 0, v5
	v_fma_f32 v2, v178, v2, 0
	v_fma_f32 v3, v179, v3, 0
	v_max_f32_e32 v6, 0, v6
	v_max_f32_e32 v7, 0, v7
	v_fmac_f32_e32 v2, v38, v4
	v_fmac_f32_e32 v3, v39, v5
	v_max_f32_e32 v8, 0, v8
	v_max_f32_e32 v9, 0, v9
	v_fmac_f32_e32 v2, v180, v6
	v_fmac_f32_e32 v3, v181, v7
	v_max_f32_e32 v10, 0, v10
	v_max_f32_e32 v11, 0, v11
	v_fmac_f32_e32 v2, v40, v8
	v_fmac_f32_e32 v3, v41, v9
	v_max_f32_e32 v12, 0, v12
	v_max_f32_e32 v13, 0, v13
	v_fmac_f32_e32 v2, v182, v10
	v_fmac_f32_e32 v3, v183, v11
	v_max_f32_e32 v14, 0, v14
	v_max_f32_e32 v15, 0, v15
	v_fmac_f32_e32 v2, v34, v12
	v_fmac_f32_e32 v3, v35, v13
	v_max_f32_e32 v16, 0, v16
	v_max_f32_e32 v17, 0, v17
	v_fmac_f32_e32 v2, v184, v14
	v_fmac_f32_e32 v3, v185, v15
	v_fma_f32 v4, v36, v16, v2
	v_fma_f32 v5, v37, v17, v3
	v_ashrrev_i32_e32 v2, 31, v4
	v_ashrrev_i32_e32 v6, 31, v5
	v_or_b32_e32 v2, 0x80000000, v2
	v_or_b32_e32 v6, 0x80000000, v6
	v_xor_b32_e32 v3, v4, v2
	v_xor_b32_e32 v2, v5, v6
	v_cmp_gt_u32_e64 s[4:5], v3, v0
	v_cmp_gt_u32_e64 s[6:7], v2, v94
	s_and_b64 s[10:11], s[0:1], s[4:5]
	s_and_b64 s[4:5], s[2:3], s[6:7]
	s_or_b64 s[6:7], s[10:11], s[4:5]
	s_cbranch_scc0 .LBB0_511
	s_and_b64 s[2:3], s[10:11], exec
	s_and_b64 s[0:1], s[4:5], exec
	s_and_saveexec_b64 s[6:7], s[10:11]
	s_cbranch_execz .LBB0_508
	v_mov_b32_e32 v4, s3
	v_mov_b32_e32 v5, s2
	v_cndmask_b32_e32 v4, v4, v5, vcc
	v_and_b32_e32 v4, v4, v218
	v_bcnt_u32_b32 v4, v4, 0
	v_cndmask_b32_e32 v5, v187, v173, vcc
	v_add3_u32 v4, v5, v214, v4
	v_lshl_add_u32 v5, v4, 2, v190
	ds_write_b32 v5, v3
	v_lshlrev_b32_e32 v3, 1, v4
	v_sub_u32_e32 v3, v5, v3
	ds_write_b16 v3, v78 offset:10240

; DI f32x16 mfma32(bf16x8 a, bf16x8 b, f32x16 c) { return __builtin_amdgcn_mfma_f32_32x32x16_bf16(a, b, c, 0, 0, 0); }
; DI u32 mono_key(float f) { u32 u = __float_as_uint(f); return (u & 0x80000000u) ? ~u : (u | 0x80000000u); }
; DI void dsa_item(const Params& p, int l, int tile32, int b, char* smem) {
;     ...
;       for (int t = 0; t < 4; ++t) {
;         const int key = (g * 4 + t) * 32 + c31;
;         f32x16 acc;
; #pragma unroll
;         for (int j = 0; j < 16; ++j) acc[j] = 0.f;
; #pragma unroll
;         for (int s = 0; s < 4; ++s) acc = mfma32(qa[s], kc[t][s], acc);
;         f32x2 ss2 = f32x2{0.f, 0.f};
; #pragma unroll
;         for (int hq = 0; hq < 8; ++hq) {
;           const f32x2 rr = f32x2{__builtin_amdgcn_fmed3f(acc[2 * hq], 0.f, 3.0e38f), __builtin_amdgcn_fmed3f(acc[2 * hq + 1], 0.f, 3.0e38f)};
;           ss2 = __builtin_elementwise_fma(wq2[hq], rr, ss2);
;         }
;         const float s0 = ss2.x, s1 = ss2.y;
;         const u32 k0 = mono_key(s0), k1 = mono_key(s1);
;         const bool c0 = (key <= qpos0) && (k0 > tauA), c1 = (key <= qpos0 + 1) && (k1 > tauB);
;         const u64 m0 = __ballot(c0), m1 = __ballot(c1);
;         if (m0 | m1) {
;           const u32 h0 = hh ? (u32)(m0 >> 32) : (u32)m0, h1 = hh ? (u32)(m1 >> 32) : (u32)m1;
;           const int pA = (hh ? cnt2 : cnt0) + __popc(h0 & lmask), pB = (hh ? cnt3 : cnt1) + __popc(h1 & lmask);
;           if (c0) { ckey[(2 * hh) * DCAP + pA] = k0; cidx[(2 * hh) * DCAP + pA] = (u16)key; }
;           if (c1) { ckey[(2 * hh + 1) * DCAP + pB] = k1; cidx[(2 * hh + 1) * DCAP + pB] = (u16)key; }
;           cnt0 += __popc((u32)m0); cnt2 += __popc((u32)(m0 >> 32));
;           cnt1 += __popc((u32)m1); cnt3 += __popc((u32)(m1 >> 32));
;         }
.LBB0_511:
	v_mfma_f32_32x32x16_bf16 v[2:17], v[18:21], v[70:73], 0
	v_mfma_f32_32x32x16_bf16 v[2:17], v[22:25], v[66:69], v[2:17]
	v_mfma_f32_32x32x16_bf16 v[2:17], v[26:29], v[62:65], v[2:17]
	v_mfma_f32_32x32x16_bf16 v[2:17], v[30:33], v[58:61], v[2:17]
	v_or_b32_e32 v62, 64, v95
	v_cmp_le_i32_e64 s[0:1], v62, v217
	v_cmp_le_i32_e64 s[2:3], v62, v219
	s_nop 8
	v_max_f32_e32 v2, 0, v2
	v_max_f32_e32 v3, 0, v3
	v_max_f32_e32 v4, 0, v4
	v_max_f32_e32 v5, 0, v5
	v_fma_f32 v2, v178, v2, 0
	v_fma_f32 v3, v179, v3, 0
	v_max_f32_e32 v6, 0, v6
	v_max_f32_e32 v7, 0, v7
	v_fmac_f32_e32 v2, v38, v4
	v_fmac_f32_e32 v3, v39, v5
	v_max_f32_e32 v8, 0, v8
	v_max_f32_e32 v9, 0, v9
	v_fmac_f32_e32 v2, v180, v6
	v_fmac_f32_e32 v3, v181, v7
	v_max_f32_e32 v10, 0, v10
	v_max_f32_e32 v11, 0, v11
	v_fmac_f32_e32 v2, v40, v8
	v_fmac_f32_e32 v3, v41, v9
	v_max_f32_e32 v12, 0, v12
	v_max_f32_e32 v13, 0, v13
	v_fmac_f32_e32 v2, v182, v10
	v_fmac_f32_e32 v3, v183, v11
	v_max_f32_e32 v14, 0, v14
	v_max_f32_e32 v15, 0, v15
	v_fmac_f32_e32 v2, v34, v12
	v_fmac_f32_e32 v3, v35, v13
	v_max_f32_e32 v16, 0, v16
	v_max_f32_e32 v17, 0, v17
	v_fmac_f32_e32 v2, v184, v14
	v_fmac_f32_e32 v3, v185, v15
	v_fma_f32 v4, v36, v16, v2
	v_fma_f32 v5, v37, v17, v3
	v_ashrrev_i32_e32 v2, 31, v4
	v_ashrrev_i32_e32 v6, 31, v5
	v_or_b32_e32 v2, 0x80000000, v2
	v_or_b32_e32 v6, 0x80000000, v6
	v_xor_b32_e32 v3, v4, v2
	v_xor_b32_e32 v2, v5, v6
	v_cmp_gt_u32_e64 s[4:5], v3, v0
	v_cmp_gt_u32_e64 s[6:7], v2, v94
	s_and_b64 s[10:11], s[0:1], s[4:5]
	s_and_b64 s[4:5], s[2:3], s[6:7]
	s_or_b64 s[6:7], s[10:11], s[4:5]
	s_cbranch_scc0 .LBB0_517
	s_and_b64 s[2:3], s[10:11], exec
	s_and_b64 s[0:1], s[4:5], exec
	s_and_saveexec_b64 s[6:7], s[10:11]
	s_cbranch_execz .LBB0_514
	v_mov_b32_e32 v4, s3
	v_mov_b32_e32 v5, s2
	v_cndmask_b32_e32 v4, v4, v5, vcc
	v_and_b32_e32 v4, v4, v218
	v_bcnt_u32_b32 v4, v4, 0
	v_cndmask_b32_e32 v5, v187, v173, vcc
	v_add3_u32 v4, v5, v214, v4
	v_lshl_add_u32 v5, v4, 2, v190
	ds_write_b32 v5, v3
	v_lshlrev_b32_e32 v3, 1, v4
	v_sub_u32_e32 v3, v5, v3
	ds_write_b16 v3, v62 offset:10240

; DI f32x16 mfma32(bf16x8 a, bf16x8 b, f32x16 c) { return __builtin_amdgcn_mfma_f32_32x32x16_bf16(a, b, c, 0, 0, 0); }
; DI u32 mono_key(float f) { u32 u = __float_as_uint(f); return (u & 0x80000000u) ? ~u : (u | 0x80000000u); }
; DI void dsa_item(const Params& p, int l, int tile32, int b, char* smem) {
;     ...
;       for (int t = 0; t < 4; ++t) {
;         const int key = (g * 4 + t) * 32 + c31;
;         f32x16 acc;
; #pragma unroll
;         for (int j = 0; j < 16; ++j) acc[j] = 0.f;
; #pragma unroll
;         for (int s = 0; s < 4; ++s) acc = mfma32(qa[s], kc[t][s], acc);
;         f32x2 ss2 = f32x2{0.f, 0.f};
; #pragma unroll
;         for (int hq = 0; hq < 8; ++hq) {
;           const f32x2 rr = f32x2{__builtin_amdgcn_fmed3f(acc[2 * hq], 0.f, 3.0e38f), __builtin_amdgcn_fmed3f(acc[2 * hq + 1], 0.f, 3.0e38f)};
;           ss2 = __builtin_elementwise_fma(wq2[hq], rr, ss2);
;         }
;         const float s0 = ss2.x, s1 = ss2.y;
;         const u32 k0 = mono_key(s0), k1 = mono_key(s1);
;         const bool c0 = (key <= qpos0) && (k0 > tauA), c1 = (key <= qpos0 + 1) && (k1 > tauB);
;         const u64 m0 = __ballot(c0), m1 = __ballot(c1);
;         if (m0 | m1) {
;           const u32 h0 = hh ? (u32)(m0 >> 32) : (u32)m0, h1 = hh ? (u32)(m1 >> 32) : (u32)m1;
;           const int pA = (hh ? cnt2 : cnt0) + __popc(h0 & lmask), pB = (hh ? cnt3 : cnt1) + __popc(h1 & lmask);
;           if (c0) { ckey[(2 * hh) * DCAP + pA] = k0; cidx[(2 * hh) * DCAP + pA] = (u16)key; }
;           if (c1) { ckey[(2 * hh + 1) * DCAP + pB] = k1; cidx[(2 * hh + 1) * DCAP + pB] = (u16)key; }
;           cnt0 += __popc((u32)m0); cnt2 += __popc((u32)(m0 >> 32));
;           cnt1 += __popc((u32)m1); cnt3 += __popc((u32)(m1 >> 32));
;         }
.LBB0_517:
	v_mfma_f32_32x32x16_bf16 v[2:17], v[18:21], v[54:57], 0
	v_mfma_f32_32x32x16_bf16 v[2:17], v[22:25], v[50:53], v[2:17]
	v_mfma_f32_32x32x16_bf16 v[2:17], v[26:29], v[46:49], v[2:17]
	v_mfma_f32_32x32x16_bf16 v[2:17], v[30:33], v[42:45], v[2:17]
	v_or_b32_e32 v46, 0x60, v95
	v_cmp_le_i32_e64 s[0:1], v46, v217
	v_cmp_le_i32_e64 s[2:3], v46, v219
	s_nop 8
	v_max_f32_e32 v2, 0, v2
	v_max_f32_e32 v3, 0, v3
	v_max_f32_e32 v4, 0, v4
	v_max_f32_e32 v5, 0, v5
	v_fma_f32 v2, v178, v2, 0
	v_fma_f32 v3, v179, v3, 0
	v_max_f32_e32 v6, 0, v6
	v_max_f32_e32 v7, 0, v7
	v_fmac_f32_e32 v2, v38, v4
	v_fmac_f32_e32 v3, v39, v5
	v_max_f32_e32 v8, 0, v8
	v_max_f32_e32 v9, 0, v9
	v_fmac_f32_e32 v2, v180, v6
	v_fmac_f32_e32 v3, v181, v7
	v_max_f32_e32 v10, 0, v10
	v_max_f32_e32 v11, 0, v11
	v_fmac_f32_e32 v2, v40, v8
	v_fmac_f32_e32 v3, v41, v9
	v_max_f32_e32 v12, 0, v12
	v_max_f32_e32 v13, 0, v13
	v_fmac_f32_e32 v2, v182, v10
	v_fmac_f32_e32 v3, v183, v11
	v_max_f32_e32 v14, 0, v14
	v_max_f32_e32 v15, 0, v15
	v_fmac_f32_e32 v2, v34, v12
	v_fmac_f32_e32 v3, v35, v13
	v_max_f32_e32 v16, 0, v16
	v_max_f32_e32 v17, 0, v17
	v_fmac_f32_e32 v2, v184, v14
	v_fmac_f32_e32 v3, v185, v15
	v_fma_f32 v4, v36, v16, v2
	v_fma_f32 v5, v37, v17, v3
	v_ashrrev_i32_e32 v2, 31, v4
	v_ashrrev_i32_e32 v6, 31, v5
	v_or_b32_e32 v2, 0x80000000, v2
	v_or_b32_e32 v6, 0x80000000, v6
	v_xor_b32_e32 v3, v4, v2
	v_xor_b32_e32 v2, v5, v6
	v_cmp_gt_u32_e64 s[4:5], v3, v0
	v_cmp_gt_u32_e64 s[6:7], v2, v94
	s_and_b64 s[10:11], s[0:1], s[4:5]
	s_and_b64 s[4:5], s[2:3], s[6:7]
	s_or_b64 s[6:7], s[10:11], s[4:5]
	s_cbranch_scc0 .LBB0_374
	s_and_b64 s[2:3], s[10:11], exec
	s_and_b64 s[0:1], s[4:5], exec
	s_and_saveexec_b64 s[6:7], s[10:11]
	s_cbranch_execz .LBB0_520
	v_mov_b32_e32 v0, s3
	v_mov_b32_e32 v4, s2
	v_cndmask_b32_e32 v0, v0, v4, vcc
	v_and_b32_e32 v0, v0, v218
	v_bcnt_u32_b32 v0, v0, 0
	v_cndmask_b32_e32 v4, v187, v173, vcc
	v_add3_u32 v0, v4, v214, v0
	v_lshl_add_u32 v4, v0, 2, v190
	v_lshlrev_b32_e32 v0, 1, v0
	v_sub_u32_e32 v0, v4, v0
	ds_write_b32 v4, v3
	ds_write_b16 v0, v46 offset:10240
